# latent attention: K rows of the next row pair prefetched in the middle of the previous O += V^T P (into dead score registers); confirmed with attention phases repeated 4x
# speedup vs baseline: 1.0160x; 1.0062x over previous
.LBB0_387:
	v_lshl_add_u32 v18, s18, 7, v145
	s_waitcnt vmcnt(2)
	ds_write_b128 v136, v[4:7] offset:640
	s_waitcnt vmcnt(1)
	ds_write_b128 v136, v[8:11] offset:768
	s_waitcnt vmcnt(0)
	ds_write_b128 v136, v[12:15] offset:896
	s_waitcnt lgkmcnt(0)
	s_barrier
	v_cvt_pk_bf16_f32 v4, v166, v165
	v_cvt_pk_bf16_f32 v5, v168, v167
	v_cvt_pk_bf16_f32 v6, v171, v230
	v_cvt_pk_bf16_f32 v7, v172, v231
	ds_read_b128 v[8:11], v18
	ds_read_b128 v[12:15], v18 offset:18688
	ds_read_b128 v[114:117], v18 offset:37376
	ds_read_b128 v[164:167], v18 offset:56064
	v_lshl_add_u32 v18, s19, 7, v145
	s_waitcnt lgkmcnt(3)
	v_mfma_f32_16x16x32_bf16 v[8:11], v[8:11], v[4:7], 0
	v_lshlrev_b64 v[16:17], 11, v[16:17]
	v_lshl_add_u64 v[16:17], v[60:61], 0, v[16:17]
	s_addk_i32 s6, 0x80
	s_waitcnt lgkmcnt(2)
	v_mfma_f32_16x16x32_bf16 v[12:15], v[12:15], v[4:7], 0
	s_add_i32 s79, s79, 2
	s_add_i32 s80, s80, 2
	s_add_i32 s81, s81, -2
	s_waitcnt lgkmcnt(1)
	v_mfma_f32_16x16x32_bf16 v[114:117], v[114:117], v[4:7], 0
	s_cmpk_lg_i32 s6, 0x800
	s_waitcnt lgkmcnt(0)
	v_mfma_f32_16x16x32_bf16 v[4:7], v[164:167], v[4:7], 0
	v_cvt_pk_bf16_f32 v164, v169, v170
	v_cvt_pk_bf16_f32 v165, v173, v174
	v_cvt_pk_bf16_f32 v166, v175, v177
	v_cvt_pk_bf16_f32 v167, v179, v232
	ds_read_b128 v[168:171], v18
	ds_read_b128 v[152:155], v18 offset:18688
	ds_read_b128 v[156:159], v18 offset:37376
	ds_read_b128 v[160:163], v18 offset:56064
	v_lshl_add_u32 v18, s20, 7, v145
	s_waitcnt lgkmcnt(3)
	v_mfma_f32_16x16x32_bf16 v[8:11], v[168:171], v[164:167], v[8:11]
	s_waitcnt lgkmcnt(2)
	v_mfma_f32_16x16x32_bf16 v[12:15], v[152:155], v[164:167], v[12:15]
	s_waitcnt lgkmcnt(1)
	v_mfma_f32_16x16x32_bf16 v[114:117], v[156:159], v[164:167], v[114:117]
	s_waitcnt lgkmcnt(0)
	v_mfma_f32_16x16x32_bf16 v[4:7], v[160:163], v[164:167], v[4:7]
	v_cvt_pk_bf16_f32 v164, v176, v178
	v_cvt_pk_bf16_f32 v165, v180, v181
	v_cvt_pk_bf16_f32 v166, v182, v184
	v_cvt_pk_bf16_f32 v167, v187, v189
	ds_read_b128 v[168:171], v18
	ds_read_b128 v[152:155], v18 offset:18688
	ds_read_b128 v[156:159], v18 offset:37376
	ds_read_b128 v[160:163], v18 offset:56064
	v_lshl_add_u32 v18, s21, 7, v145
	s_waitcnt lgkmcnt(3)
	v_mfma_f32_16x16x32_bf16 v[8:11], v[168:171], v[164:167], v[8:11]
	s_waitcnt lgkmcnt(2)
	v_mfma_f32_16x16x32_bf16 v[12:15], v[152:155], v[164:167], v[12:15]
	s_waitcnt lgkmcnt(1)
	v_mfma_f32_16x16x32_bf16 v[114:117], v[156:159], v[164:167], v[114:117]
	s_waitcnt lgkmcnt(0)
	v_mfma_f32_16x16x32_bf16 v[4:7], v[160:163], v[164:167], v[4:7]
	v_cvt_pk_bf16_f32 v164, v183, v185
	v_cvt_pk_bf16_f32 v165, v186, v190
	v_cvt_pk_bf16_f32 v166, v191, v193
	v_cvt_pk_bf16_f32 v167, v196, v197
	ds_read_b128 v[168:171], v18
	ds_read_b128 v[152:155], v18 offset:18688
	ds_read_b128 v[156:159], v18 offset:37376
	ds_read_b128 v[160:163], v18 offset:56064
	v_lshl_add_u32 v18, s30, 7, v145
	s_waitcnt lgkmcnt(3)
	v_mfma_f32_16x16x32_bf16 v[8:11], v[168:171], v[164:167], v[8:11]
	s_waitcnt lgkmcnt(2)
	v_mfma_f32_16x16x32_bf16 v[12:15], v[152:155], v[164:167], v[12:15]
	s_waitcnt lgkmcnt(1)
	v_mfma_f32_16x16x32_bf16 v[114:117], v[156:159], v[164:167], v[114:117]
	s_waitcnt lgkmcnt(0)
	v_mfma_f32_16x16x32_bf16 v[4:7], v[160:163], v[164:167], v[4:7]
	v_cvt_pk_bf16_f32 v164, v192, v194
	v_cvt_pk_bf16_f32 v165, v195, v198
	v_cvt_pk_bf16_f32 v166, v199, v201
	v_cvt_pk_bf16_f32 v167, v204, v205
	ds_read_b128 v[168:171], v18
	ds_read_b128 v[152:155], v18 offset:18688
	ds_read_b128 v[156:159], v18 offset:37376
	ds_read_b128 v[160:163], v18 offset:56064
	v_lshl_add_u32 v18, s31, 7, v145
	s_waitcnt lgkmcnt(3)
	v_mfma_f32_16x16x32_bf16 v[8:11], v[168:171], v[164:167], v[8:11]
	s_waitcnt lgkmcnt(2)
	v_mfma_f32_16x16x32_bf16 v[12:15], v[152:155], v[164:167], v[12:15]
	s_waitcnt lgkmcnt(1)
	v_mfma_f32_16x16x32_bf16 v[114:117], v[156:159], v[164:167], v[114:117]
	s_waitcnt lgkmcnt(0)
	v_mfma_f32_16x16x32_bf16 v[4:7], v[160:163], v[164:167], v[4:7]
	v_cvt_pk_bf16_f32 v164, v200, v202
	v_cvt_pk_bf16_f32 v165, v203, v206
	v_cvt_pk_bf16_f32 v166, v207, v209
	v_cvt_pk_bf16_f32 v167, v212, v233
	ds_read_b128 v[168:171], v18
	ds_read_b128 v[152:155], v18 offset:18688
	ds_read_b128 v[156:159], v18 offset:37376
	ds_read_b128 v[160:163], v18 offset:56064
	v_lshl_add_u32 v18, s33, 7, v145
	s_waitcnt lgkmcnt(3)
	v_mfma_f32_16x16x32_bf16 v[8:11], v[168:171], v[164:167], v[8:11]
	s_waitcnt lgkmcnt(2)
	v_mfma_f32_16x16x32_bf16 v[12:15], v[152:155], v[164:167], v[12:15]
	s_waitcnt lgkmcnt(1)
	v_mfma_f32_16x16x32_bf16 v[114:117], v[156:159], v[164:167], v[114:117]
	s_waitcnt lgkmcnt(0)
	v_mfma_f32_16x16x32_bf16 v[4:7], v[160:163], v[164:167], v[4:7]
	v_cvt_pk_bf16_f32 v164, v208, v210
	v_cvt_pk_bf16_f32 v165, v211, v214
	v_cvt_pk_bf16_f32 v166, v215, v217
	v_cvt_pk_bf16_f32 v167, v220, v234
	ds_read_b128 v[168:171], v18
	ds_read_b128 v[152:155], v18 offset:18688
	ds_read_b128 v[156:159], v18 offset:37376
	ds_read_b128 v[160:163], v18 offset:56064
	v_lshl_add_u32 v18, s34, 7, v145
	s_waitcnt lgkmcnt(3)
	v_mfma_f32_16x16x32_bf16 v[8:11], v[168:171], v[164:167], v[8:11]
	s_waitcnt lgkmcnt(2)
	v_mfma_f32_16x16x32_bf16 v[12:15], v[152:155], v[164:167], v[12:15]
	s_waitcnt lgkmcnt(1)
	v_mfma_f32_16x16x32_bf16 v[114:117], v[156:159], v[164:167], v[114:117]
	s_waitcnt lgkmcnt(0)
	v_mfma_f32_16x16x32_bf16 v[4:7], v[160:163], v[164:167], v[4:7]
	v_cvt_pk_bf16_f32 v164, v213, v216
	v_cvt_pk_bf16_f32 v165, v218, v221
	v_cvt_pk_bf16_f32 v166, v222, v224
	v_cvt_pk_bf16_f32 v167, v226, v229
	ds_read_b128 v[168:171], v18
	ds_read_b128 v[152:155], v18 offset:18688
	ds_read_b128 v[156:159], v18 offset:37376
	ds_read_b128 v[160:163], v18 offset:56064
	s_waitcnt lgkmcnt(3)
	v_mfma_f32_16x16x32_bf16 v[8:11], v[168:171], v[164:167], v[8:11]
	s_waitcnt lgkmcnt(2)
	v_mfma_f32_16x16x32_bf16 v[12:15], v[152:155], v[164:167], v[12:15]
	s_waitcnt lgkmcnt(1)
	v_mfma_f32_16x16x32_bf16 v[114:117], v[156:159], v[164:167], v[114:117]
	s_waitcnt lgkmcnt(0)
	v_mfma_f32_16x16x32_bf16 v[4:7], v[160:163], v[164:167], v[4:7]
	v_med3_i32 v172, s79, 4, 60
	v_lshlrev_b32_e32 v208, 6, v172
	v_or_b32_e32 v196, v208, v137
	v_add_u32_e32 v209, 0xffffff00, v208
	v_ashrrev_i32_e32 v197, 31, v196
	v_add_u32_e32 v172, v209, v137
	v_add_u32_e32 v176, v55, v208
	v_add_u32_e32 v180, v140, v208
	v_add_u32_e32 v184, v141, v208
	v_lshlrev_b64 v[192:193], 12, v[196:197]
	v_or_b32_e32 v196, 64, v196
	v_add_u32_e32 v200, v142, v208
	v_add_u32_e32 v204, v143, v208
	v_ashrrev_i32_e32 v173, 31, v172
	v_ashrrev_i32_e32 v177, 31, v176
	v_ashrrev_i32_e32 v181, 31, v180
	v_ashrrev_i32_e32 v185, 31, v184
	v_ashrrev_i32_e32 v197, 31, v196
	v_ashrrev_i32_e32 v201, 31, v200
	v_ashrrev_i32_e32 v205, 31, v204
	v_lshlrev_b64 v[172:173], 12, v[172:173]
	v_lshlrev_b64 v[176:177], 12, v[176:177]
	v_lshlrev_b64 v[180:181], 12, v[180:181]
	v_lshlrev_b64 v[184:185], 12, v[184:185]
	v_lshlrev_b64 v[196:197], 12, v[196:197]
	v_lshlrev_b64 v[200:201], 12, v[200:201]
	v_lshlrev_b64 v[204:205], 12, v[204:205]
	v_lshl_add_u64 v[172:173], v[78:79], 0, v[172:173]
	v_lshl_add_u64 v[176:177], v[78:79], 0, v[176:177]
	v_lshl_add_u64 v[180:181], v[78:79], 0, v[180:181]
	v_lshl_add_u64 v[184:185], v[78:79], 0, v[184:185]
	v_lshl_add_u64 v[192:193], v[78:79], 0, v[192:193]
	v_lshl_add_u64 v[196:197], v[78:79], 0, v[196:197]
	v_lshl_add_u64 v[200:201], v[78:79], 0, v[200:201]
	v_lshl_add_u64 v[204:205], v[78:79], 0, v[204:205]
	global_load_dwordx4 v[172:175], v[172:173], off offset:2048
	global_load_dwordx4 v[176:179], v[176:177], off offset:2048
	global_load_dwordx4 v[180:183], v[180:181], off offset:2048
	s_cmp_gt_u32 s79, 59
	global_load_dwordx4 v[184:187], v[184:185], off offset:2048
	s_nop 0
	global_load_dwordx4 v[192:195], v[192:193], off offset:2048
	s_nop 0
	global_load_dwordx4 v[196:199], v[196:197], off offset:2048
	s_nop 0
	global_load_dwordx4 v[200:203], v[200:201], off offset:2048
	s_nop 0
	global_load_dwordx4 v[204:207], v[204:205], off offset:2048
	s_cbranch_scc1 .Lke_skip9b
	v_add_u32_e32 v230, v144, v208
	v_ashrrev_i32_e32 v231, 31, v230
	v_lshlrev_b64 v[230:231], 12, v[230:231]
	v_lshl_add_u64 v[230:231], v[78:79], 0, v[230:231]
	global_load_dwordx4 v[230:233], v[230:231], off offset:2048
.Lke_skip9b:
	v_cvt_pk_bf16_f32 v164, v219, v223
	v_cvt_pk_bf16_f32 v165, v225, v227
	v_cvt_pk_bf16_f32 v166, v228, v235
	v_cvt_pk_bf16_f32 v167, v236, v237
	ds_read_b128 v[168:171], v135 offset:36864
	ds_read_b128 v[152:155], v135 offset:45312
	ds_read_b128 v[156:159], v135 offset:53760
	ds_read_b128 v[160:163], v135 offset:62208
	s_waitcnt lgkmcnt(3)
	v_mfma_f32_16x16x32_bf16 v[8:11], v[168:171], v[164:167], v[8:11]
	s_waitcnt lgkmcnt(2)
	v_mfma_f32_16x16x32_bf16 v[12:15], v[152:155], v[164:167], v[12:15]
	s_waitcnt lgkmcnt(1)
	v_mfma_f32_16x16x32_bf16 v[114:117], v[156:159], v[164:167], v[114:117]
	s_waitcnt lgkmcnt(0)
	v_mfma_f32_16x16x32_bf16 v[4:7], v[160:163], v[164:167], v[4:7]
	v_cvt_pk_bf16_f32 v164, v22, v23
	v_cvt_pk_bf16_f32 v165, v20, v26
	v_cvt_pk_bf16_f32 v166, v27, v30
	v_cvt_pk_bf16_f32 v167, v31, v238
	ds_read_b128 v[168:171], v135 offset:36928
	s_waitcnt lgkmcnt(0)
	v_mfma_f32_16x16x32_bf16 v[8:11], v[168:171], v[164:167], v[8:11]
	ds_read_b128 v[168:171], v135 offset:45376
	s_waitcnt lgkmcnt(0)
	v_mfma_f32_16x16x32_bf16 v[12:15], v[168:171], v[164:167], v[12:15]
	ds_read_b128 v[168:171], v135 offset:53824
	s_waitcnt lgkmcnt(0)
	v_mfma_f32_16x16x32_bf16 v[114:117], v[168:171], v[164:167], v[114:117]
	ds_read_b128 v[168:171], v135 offset:62272
	v_cvt_pk_bf16_f32 v18, v21, v24
	v_cvt_pk_bf16_f32 v19, v25, v28
	v_cvt_pk_bf16_f32 v20, v34, v35
	v_cvt_pk_bf16_f32 v21, v82, v83
	ds_read_b128 v[22:25], v135 offset:36992
	s_waitcnt lgkmcnt(0)
	v_mfma_f32_16x16x32_bf16 v[8:11], v[22:25], v[18:21], v[8:11]
	ds_read_b128 v[22:25], v135 offset:45440
	s_waitcnt lgkmcnt(0)
	v_mfma_f32_16x16x32_bf16 v[12:15], v[22:25], v[18:21], v[12:15]
	ds_read_b128 v[22:25], v135 offset:53888
	s_waitcnt lgkmcnt(0)
	v_mfma_f32_16x16x32_bf16 v[22:25], v[22:25], v[18:21], v[114:117]
	s_nop 2
	ds_read_b128 v[114:117], v135 offset:62336
	v_mfma_f32_16x16x32_bf16 v[4:7], v[168:171], v[164:167], v[4:7]
	s_waitcnt lgkmcnt(0)
	v_mfma_f32_16x16x32_bf16 v[4:7], v[114:117], v[18:21], v[4:7]
	v_cvt_pk_bf16_f32 v18, v29, v32
	v_cvt_pk_bf16_f32 v19, v33, v80
	v_cvt_pk_bf16_f32 v20, v86, v87
	v_cvt_pk_bf16_f32 v21, v91, v239
	ds_read_b128 v[26:29], v135 offset:37056
	ds_read_b128 v[152:155], v135 offset:45504
	ds_read_b128 v[156:159], v135 offset:53952
	ds_read_b128 v[160:163], v135 offset:62400
	s_waitcnt lgkmcnt(3)
	v_mfma_f32_16x16x32_bf16 v[8:11], v[26:29], v[18:21], v[8:11]
	s_waitcnt lgkmcnt(2)
	v_mfma_f32_16x16x32_bf16 v[12:15], v[152:155], v[18:21], v[12:15]
	s_waitcnt lgkmcnt(1)
	v_mfma_f32_16x16x32_bf16 v[22:25], v[156:159], v[18:21], v[22:25]
	s_waitcnt lgkmcnt(0)
	v_mfma_f32_16x16x32_bf16 v[4:7], v[160:163], v[18:21], v[4:7]
	v_cvt_pk_bf16_f32 v18, v81, v84
	v_cvt_pk_bf16_f32 v19, v90, v89
	v_cvt_pk_bf16_f32 v20, v94, v98
	v_cvt_pk_bf16_f32 v21, v240, v242
	ds_read_b128 v[26:29], v135 offset:37120
	ds_read_b128 v[152:155], v135 offset:45568
	ds_read_b128 v[156:159], v135 offset:54016
	ds_read_b128 v[160:163], v135 offset:62464
	s_waitcnt lgkmcnt(3)
	v_mfma_f32_16x16x32_bf16 v[8:11], v[26:29], v[18:21], v[8:11]
	s_waitcnt lgkmcnt(2)
	v_mfma_f32_16x16x32_bf16 v[12:15], v[152:155], v[18:21], v[12:15]
	s_waitcnt lgkmcnt(1)
	v_mfma_f32_16x16x32_bf16 v[22:25], v[156:159], v[18:21], v[22:25]
	s_waitcnt lgkmcnt(0)
	v_mfma_f32_16x16x32_bf16 v[4:7], v[160:163], v[18:21], v[4:7]
	v_cvt_pk_bf16_f32 v18, v92, v93
	v_cvt_pk_bf16_f32 v19, v102, v241
	v_cvt_pk_bf16_f32 v20, v243, v244
	v_cvt_pk_bf16_f32 v21, v245, v246
	ds_read_b128 v[26:29], v135 offset:37184
	ds_read_b128 v[152:155], v135 offset:45632
	ds_read_b128 v[156:159], v135 offset:54080
	ds_read_b128 v[160:163], v135 offset:62528
	s_waitcnt lgkmcnt(3)
	v_mfma_f32_16x16x32_bf16 v[8:11], v[26:29], v[18:21], v[8:11]
	s_waitcnt lgkmcnt(2)
	v_mfma_f32_16x16x32_bf16 v[12:15], v[152:155], v[18:21], v[12:15]
	s_waitcnt lgkmcnt(1)
	v_mfma_f32_16x16x32_bf16 v[22:25], v[156:159], v[18:21], v[22:25]
	s_waitcnt lgkmcnt(0)
	v_mfma_f32_16x16x32_bf16 v[4:7], v[160:163], v[18:21], v[4:7]
	v_cvt_pk_bf16_f32 v18, v105, v108
	v_cvt_pk_bf16_f32 v19, v106, v107
	v_cvt_pk_bf16_f32 v20, v109, v112
	v_cvt_pk_bf16_f32 v21, v110, v111
	ds_read_b128 v[26:29], v135 offset:37248
	ds_read_b128 v[152:155], v135 offset:45696
	ds_read_b128 v[156:159], v135 offset:54144
	ds_read_b128 v[160:163], v135 offset:62592
	s_waitcnt lgkmcnt(3)
	v_mfma_f32_16x16x32_bf16 v[8:11], v[26:29], v[18:21], v[8:11]
	s_waitcnt lgkmcnt(2)
	v_mfma_f32_16x16x32_bf16 v[12:15], v[152:155], v[18:21], v[12:15]
	s_waitcnt lgkmcnt(1)
	v_mfma_f32_16x16x32_bf16 v[22:25], v[156:159], v[18:21], v[22:25]
	s_waitcnt lgkmcnt(0)
	v_mfma_f32_16x16x32_bf16 v[4:7], v[160:163], v[18:21], v[4:7]
	v_cvt_pk_bf16_f32 v18, v95, v97
	v_cvt_pk_bf16_f32 v19, v96, v99
	v_cvt_pk_bf16_f32 v20, v100, v101
	v_cvt_pk_bf16_f32 v21, v103, v104
	ds_read_b128 v[26:29], v135 offset:37312
	ds_read_b128 v[152:155], v135 offset:45760
	ds_read_b128 v[156:159], v135 offset:54208
	ds_read_b128 v[160:163], v135 offset:62656
	s_waitcnt lgkmcnt(3)
	v_mfma_f32_16x16x32_bf16 v[8:11], v[26:29], v[18:21], v[8:11]
	s_waitcnt lgkmcnt(2)
	v_mfma_f32_16x16x32_bf16 v[12:15], v[152:155], v[18:21], v[12:15]
	s_waitcnt lgkmcnt(1)
	v_mfma_f32_16x16x32_bf16 v[22:25], v[156:159], v[18:21], v[22:25]
	s_waitcnt lgkmcnt(0)
	v_mfma_f32_16x16x32_bf16 v[4:7], v[160:163], v[18:21], v[4:7]
	v_add_f32_e32 v18, v85, v88
	v_div_scale_f32 v19, s[16:17], v18, v18, 1.0
	v_rcp_f32_e32 v20, v19
	s_nop 0
	v_fma_f32 v21, -v19, v20, 1.0
	v_fmac_f32_e32 v20, v21, v20
	v_div_scale_f32 v21, vcc, 1.0, v18, 1.0
	v_mul_f32_e32 v26, v21, v20
	v_fma_f32 v27, -v19, v26, v21
	v_fmac_f32_e32 v26, v27, v20
	v_fma_f32 v19, -v19, v26, v21
	v_div_fmas_f32 v19, v19, v20, v26
	v_div_fixup_f32 v18, v19, v18, 1.0
	v_pk_mul_f32 v[10:11], v[18:19], v[10:11] op_sel_hi:[0,1]
	v_pk_mul_f32 v[8:9], v[18:19], v[8:9] op_sel_hi:[0,1]
	v_cvt_pk_bf16_f32 v8, v8, v9
	v_cvt_pk_bf16_f32 v9, v10, v11
	v_pk_mul_f32 v[10:11], v[18:19], v[12:13] op_sel_hi:[0,1]
	global_store_dwordx2 v[16:17], v[8:9], off
	v_pk_mul_f32 v[8:9], v[18:19], v[14:15] op_sel_hi:[0,1]
	v_cvt_pk_bf16_f32 v10, v10, v11
	v_cvt_pk_bf16_f32 v11, v8, v9
	global_store_dwordx2 v[16:17], v[10:11], off offset:32
	v_pk_mul_f32 v[10:11], v[18:19], v[22:23] op_sel_hi:[0,1]
	v_pk_mul_f32 v[4:5], v[18:19], v[4:5] op_sel_hi:[0,1]
	v_pk_mul_f32 v[8:9], v[18:19], v[24:25] op_sel_hi:[0,1]
	v_cvt_pk_bf16_f32 v10, v10, v11
	v_cvt_pk_bf16_f32 v11, v8, v9
	global_store_dwordx2 v[16:17], v[10:11], off offset:64
	v_pk_mul_f32 v[6:7], v[18:19], v[6:7] op_sel_hi:[0,1]
	v_cvt_pk_bf16_f32 v4, v4, v5
	v_cvt_pk_bf16_f32 v5, v6, v7
	global_store_dwordx2 v[16:17], v[4:5], off offset:96
	s_cmpk_lg_i32 s6, 0x800
	s_cbranch_scc0 .LBB0_375
	s_branch .Lk388r
.LBB0_388:
	v_med3_i32 v172, s79, 4, 60
	v_lshlrev_b32_e32 v208, 6, v172
	v_or_b32_e32 v196, v208, v137
	v_add_u32_e32 v209, 0xffffff00, v208
	v_ashrrev_i32_e32 v197, 31, v196
	v_add_u32_e32 v172, v209, v137
	v_add_u32_e32 v176, v55, v208
	v_add_u32_e32 v180, v140, v208
	v_add_u32_e32 v184, v141, v208
	v_lshlrev_b64 v[192:193], 12, v[196:197]
	v_or_b32_e32 v196, 64, v196
	v_add_u32_e32 v200, v142, v208
	v_add_u32_e32 v204, v143, v208
	v_ashrrev_i32_e32 v173, 31, v172
	v_ashrrev_i32_e32 v177, 31, v176
	v_ashrrev_i32_e32 v181, 31, v180
	v_ashrrev_i32_e32 v185, 31, v184
	v_ashrrev_i32_e32 v197, 31, v196
	v_ashrrev_i32_e32 v201, 31, v200
	v_ashrrev_i32_e32 v205, 31, v204
	v_lshlrev_b64 v[172:173], 12, v[172:173]
	v_lshlrev_b64 v[176:177], 12, v[176:177]
	v_lshlrev_b64 v[180:181], 12, v[180:181]
	v_lshlrev_b64 v[184:185], 12, v[184:185]
	v_lshlrev_b64 v[196:197], 12, v[196:197]
	v_lshlrev_b64 v[200:201], 12, v[200:201]
	v_lshlrev_b64 v[204:205], 12, v[204:205]
	v_lshl_add_u64 v[172:173], v[78:79], 0, v[172:173]
	v_lshl_add_u64 v[176:177], v[78:79], 0, v[176:177]
	v_lshl_add_u64 v[180:181], v[78:79], 0, v[180:181]
	v_lshl_add_u64 v[184:185], v[78:79], 0, v[184:185]
	v_lshl_add_u64 v[192:193], v[78:79], 0, v[192:193]
	v_lshl_add_u64 v[196:197], v[78:79], 0, v[196:197]
	v_lshl_add_u64 v[200:201], v[78:79], 0, v[200:201]
	v_lshl_add_u64 v[204:205], v[78:79], 0, v[204:205]
	global_load_dwordx4 v[172:175], v[172:173], off offset:2048
	global_load_dwordx4 v[176:179], v[176:177], off offset:2048
	global_load_dwordx4 v[180:183], v[180:181], off offset:2048
	s_cmp_gt_u32 s79, 59
	global_load_dwordx4 v[184:187], v[184:185], off offset:2048
	s_nop 0
	global_load_dwordx4 v[192:195], v[192:193], off offset:2048
	s_nop 0
	global_load_dwordx4 v[196:199], v[196:197], off offset:2048
	s_nop 0
	global_load_dwordx4 v[200:203], v[200:201], off offset:2048
	s_nop 0
	global_load_dwordx4 v[204:207], v[204:205], off offset:2048
	s_cbranch_scc1 .Lke_skip9a
	v_add_u32_e32 v230, v144, v208
	v_ashrrev_i32_e32 v231, 31, v230
	v_lshlrev_b64 v[230:231], 12, v[230:231]
	v_lshl_add_u64 v[230:231], v[78:79], 0, v[230:231]
	global_load_dwordx4 v[230:233], v[230:231], off offset:2048

.Lk388r:
	v_mov_b32_e32 v247, 0xf149f2ca
	v_med3_i32 v4, s79, 4, 60
	v_lshlrev_b32_e32 v164, 6, v4
	s_add_i32 s16, s73, s79
	v_add_u32_e32 v148, 0xffffff00, v164
	v_readfirstlane_b32 s18, v4
	v_med3_i32 v5, s16, 4, 60
	s_nop 0
	v_readfirstlane_b32 s19, v5
	s_cmp_lt_u32 s79, 60
	s_cselect_b64 s[16:17], -1, 0
.LBB0_390:
	s_barrier
	s_waitcnt vmcnt(11)
	ds_write_b128 v124, v[172:175]
	s_waitcnt vmcnt(10)
	ds_write_b128 v124, v[176:179] offset:8192
	s_waitcnt vmcnt(9)
	ds_write_b128 v124, v[180:183] offset:16384
	s_waitcnt vmcnt(8)
	ds_write_b128 v124, v[184:187] offset:24576
	s_waitcnt vmcnt(7)
	ds_write_b128 v124, v[192:195] offset:32768
	s_waitcnt vmcnt(6)
	ds_write_b128 v124, v[196:199] offset:40960
	s_waitcnt vmcnt(5)
	ds_write_b128 v124, v[200:203] offset:49152
	v_cndmask_b32_e64 v4, 0, 1, s[16:17]
	v_cmp_ne_u32_e64 s[40:41], 1, v4
	s_andn2_b64 vcc, exec, s[16:17]
	s_waitcnt vmcnt(4)
	ds_write_b128 v124, v[204:207] offset:57344
	s_cbranch_vccnz .LBB0_392
	ds_write_b128 v129, v[230:233]
